# attention loop: one static s_setprio 1 for waves 4-7 before the KV-tile loop, reset at loop exit
# speedup vs baseline: 1.1831x; 1.1831x over previous
; __device__ __forceinline__ int opaque_tid() { int t = (int)threadIdx.x; asm volatile("" : "+v"(t)); return t; }
; __device__ __forceinline__ int v_st(int k, int c) { const int kk = (k & ~0xC) | ((k & 4) << 1) | ((k & 8) >> 1); return ((kk >> 3) * 4 + (c >> 5)) * 512 + ((kk & 7) * 32 + (c & 31)) * 2; }
; __device__ __forceinline__ int v_rd_base(int lane) { return ((lane & 3) << 3) | (((lane >> 2) & 3) << 6) | (((lane >> 4) & 1) << 5) | (((lane >> 5) & 1) << 8); }
; __device__ __forceinline__ void qkt(f32x16& p0, f32x16& p1, const bf16* Ks, const bf16x8* qr, int r32, int hi) {
;   p0 = f32x16{}; p1 = f32x16{};
;   for (int d0 = 0; d0 < 8; ++d0) { int cb = (d0 * 16 + hi * 8) * 2;
;     bf16x8 b0 = *reinterpret_cast<const bf16x8*>((const char*)Ks + KSWZ(r32, cb));
;     bf16x8 b1 = *reinterpret_cast<const bf16x8*>((const char*)Ks + KSWZ(32 + r32, cb));
;     p0 = __builtin_amdgcn_mfma_f32_32x32x16_bf16(b0, qr[d0], p0, 0, 0, 0);
;     p1 = __builtin_amdgcn_mfma_f32_32x32x16_bf16(b1, qr[d0], p1, 0, 0, 0); }
; template <typename TQ>
; __device__ __forceinline__ void attn_dense_body(const TQ* __restrict__ Qb, const bf16* __restrict__ Kh, const bf16* __restrict__ Vh,
;                                                 unsigned short* __restrict__ Ob, int seq, char* lds) {
;     ...
;   const int tid = ::opaque_tid(), wid = tid >> 6, lane = tid & 63, r32 = lane & 31, hi = lane >> 5;
;   bf16* V_lds = (bf16*)lds; bf16* K_lds = (bf16*)(lds + 2 * SHM_V);
;   float* ws = (float*)(lds + 2 * SHM_V + 2 * SHM_K) + wid * 64; float* li_l = ws; float* al_l = ws + 32;
;   float m_reg = -1e30f, l_reg = 0; f32x16 o[4] = {}; bf16x8 qr[8];
;   const TQ* Qw = Qb + (long)(wid * QBLK + r32) * LDQ + hi * 8;
; #pragma unroll
;   for (int d0 = 0; d0 < 8; ++d0) qr[d0] = SQ::tobf(SQ::ld8(Qw + d0 * 16));
;   const int sr = tid >> 4, sc = (tid & 15) * 8, vst0 = v_st(sr, sc), vst1 = v_st(32 + sr, sc);
;   const int vb0 = (int)(uintptr_t)V_lds + v_rd_base(lane);
;   struct { typename St::T vs0, vs1, ks0, ks1; } sr_[SDEPTH];
;     ...
;   f32x16 pA0, pA1, pB0, pB1; float mnA, mnB, alA, alB; bf16x8 pa0, pa1, pa2, pa3; const int NT = seq / KVBLK;
;   constexpr int SE = 0, SO = SDEPTH - 1;
;   SLOAD(SE, 0); asm volatile("s_waitcnt vmcnt(0)" ::: "memory"); SWRITE(0, SE); __syncthreads();
;   qkt(pA0, pA1, K_lds, qr, r32, hi); partialSM(pA0, pA1, m_reg, mnA, alA);
.LBB0_75:
	s_lshl_b64 s[40:41], s[0:1], 1
	v_readlane_b32 s0, v254, 41
	v_readlane_b32 s1, v254, 42
	s_add_u32 s46, s0, s40
	v_mov_b32_e32 v74, v211
	s_addc_u32 s47, s1, s41
	s_lshl_b64 s[0:1], s[38:39], 1
	s_add_u32 s38, s58, s0
	v_ashrrev_i32_e32 v16, 4, v74
	v_lshlrev_b32_e32 v22, 3, v74
	v_add_u32_e32 v18, 32, v16
	s_addc_u32 s39, s59, s1
	v_and_b32_e32 v176, 0x78, v22
	v_ashrrev_i32_e32 v17, 31, v16
	v_ashrrev_i32_e32 v19, 31, v18
	s_add_u32 s42, s24, s0
	v_lshlrev_b32_e32 v23, 1, v176
	v_lshlrev_b64 v[48:49], 8, v[16:17]
	v_lshlrev_b64 v[8:9], 8, v[18:19]
	s_addc_u32 s43, s25, s1
	v_or_b32_e32 v50, v48, v23
	v_mov_b32_e32 v51, v49
	v_or_b32_e32 v8, v8, v23
	v_ashrrev_i32_e32 v183, 6, v74
	s_waitcnt lgkmcnt(0)
	v_lshl_add_u64 v[0:1], s[42:43], 0, v[50:51]
	v_lshl_add_u64 v[4:5], s[42:43], 0, v[8:9]
	v_lshl_add_u64 v[10:11], s[38:39], 0, v[50:51]
	v_lshl_add_u64 v[12:13], s[38:39], 0, v[8:9]
	v_and_b32_e32 v179, 31, v74
	v_lshlrev_b32_e32 v178, 5, v183
	global_load_dwordx4 v[0:3], v[0:1], off
	s_nop 0
	global_load_dwordx4 v[4:7], v[4:5], off
	s_nop 0
	global_load_dwordx4 v[8:11], v[10:11], off
	s_nop 0
	global_load_dwordx4 v[12:15], v[12:13], off
	v_or_b32_e32 v20, v178, v179
	v_ashrrev_i32_e32 v21, 31, v20
	v_bfe_u32 v182, v74, 5, 1
	v_lshlrev_b64 v[20:21], 11, v[20:21]
	v_lshl_add_u64 v[20:21], s[46:47], 0, v[20:21]
	v_lshlrev_b32_e32 v208, 4, v182
	v_lshl_add_u64 v[20:21], v[20:21], 0, v[208:209]
	global_load_dwordx4 v[112:115], v[20:21], off
	global_load_dwordx4 v[108:111], v[20:21], off offset:32
	global_load_dwordx4 v[120:123], v[20:21], off offset:64
	global_load_dwordx4 v[124:127], v[20:21], off offset:96
	global_load_dwordx4 v[116:119], v[20:21], off offset:128
	global_load_dwordx4 v[104:107], v[20:21], off offset:160
	global_load_dwordx4 v[100:103], v[20:21], off offset:192
	global_load_dwordx4 v[96:99], v[20:21], off offset:224
	v_and_b32_e32 v19, 0xfffff0, v16
	v_lshlrev_b32_e32 v24, 1, v16
	v_lshrrev_b32_e32 v25, 1, v16
	v_and_b32_e32 v26, 3, v16
	v_and_or_b32 v19, v24, 8, v19
	v_and_or_b32 v24, v25, 4, v26
	v_and_b32_e32 v25, 0xfffff0, v18
	v_lshlrev_b32_e32 v26, 1, v18
	v_and_b32_e32 v17, 0x70, v74
	v_bfe_u32 v22, v22, 5, 2
	v_lshlrev_b32_e32 v16, 8, v16
	v_lshlrev_b32_e32 v18, 8, v18
	v_lshrrev_b32_e32 v19, 1, v19
	v_and_or_b32 v25, v26, 8, v25
	v_lshlrev_b32_e32 v52, 4, v74
	v_bitop3_b32 v16, v23, v16, v17 bitop3:0xde
	v_bitop3_b32 v17, v23, v18, v17 bitop3:0xde
	v_or_b32_e32 v18, v19, v22
	v_lshrrev_b32_e32 v19, 1, v25
	v_lshlrev_b32_e32 v68, 8, v179
	v_and_b32_e32 v69, 0x70, v52
	v_lshlrev_b32_e32 v24, 6, v24
	v_and_b32_e32 v28, 48, v23
	v_add_u32_e32 v189, 0, v16
	v_add_u32_e32 v190, 0, v17
	v_lshlrev_b32_e32 v16, 9, v18
	v_or_b32_e32 v17, v19, v22
	v_bitop3_b32 v27, v208, v68, v69 bitop3:0xde
	v_or3_b32 v16, v16, v24, v28
	v_lshlrev_b32_e32 v17, 9, v17
	v_or3_b32 v17, v17, v24, v28
	v_add_u32_e32 v191, 0, v16
	v_add_u32_e32 v193, 0, v27
	s_waitcnt vmcnt(0)
	v_add_u32_e32 v192, 0, v17
	s_mov_b64 s[28:29], 0x4000
	s_add_i32 s3, 0, 0x10000
	v_and_b32_e32 v71, 0xc0, v52
	v_and_b32_e32 v177, 63, v74
	v_lshlrev_b32_e32 v70, 3, v177
	s_mov_b32 s4, 0x42b504f3
	s_cmp_lg_u32 0, -1
	s_mov_b32 s72, s73
	s_mov_b32 s74, s73
	s_mov_b32 s75, s73
	s_waitcnt vmcnt(0)
	ds_write_b128 v191, v[0:3]
	s_waitcnt vmcnt(10)
	ds_write_b128 v192, v[4:7]
	s_waitcnt vmcnt(9)
	ds_write_b128 v189, v[8:11] offset:32768
	s_waitcnt vmcnt(8)
	ds_write_b128 v190, v[12:15] offset:32768
	s_waitcnt lgkmcnt(0)
	s_barrier
	ds_read_b128 v[0:3], v193 offset:32768
	ds_read_b128 v[4:7], v193 offset:40960
	s_waitcnt vmcnt(7) lgkmcnt(1)
	v_mfma_f32_32x32x16_bf16 v[16:31], v[0:3], v[112:115], 0
	v_or_b32_e32 v0, 32, v208
	v_bitop3_b32 v0, v0, v68, v69 bitop3:0xde
	v_add_u32_e32 v198, 0, v0
	v_and_b32_e32 v12, 0x3fffffc0, v74
	v_lshl_add_u64 v[8:9], v[50:51], 0, s[28:29]
	s_mov_b64 s[28:29], 0x6000
	v_lshl_add_u64 v[10:11], v[50:51], 0, s[28:29]
	s_waitcnt lgkmcnt(0)
	v_mfma_f32_32x32x16_bf16 v[32:47], v[4:7], v[112:115], 0
	ds_read_b128 v[0:3], v198 offset:32768
	ds_read_b128 v[4:7], v198 offset:40960
	v_lshl_add_u32 v184, v12, 2, s3
	v_lshl_add_u64 v[12:13], s[42:43], 0, v[8:9]
	v_lshl_add_u64 v[14:15], s[42:43], 0, v[10:11]
	s_mov_b64 s[28:29], 0x8000
	s_cselect_b32 s3, 0, 0
	s_mov_b32 s76, s73
	s_waitcnt vmcnt(6) lgkmcnt(1)
	v_mfma_f32_32x32x16_bf16 v[16:31], v[0:3], v[108:111], v[16:31]
	v_or_b32_e32 v0, 64, v208
	v_bitop3_b32 v0, v0, v68, v69 bitop3:0xde
	v_add_u32_e32 v197, 0, v0
	s_mov_b32 s77, s73
	s_mov_b32 s78, s73
	s_mov_b32 s79, s73
	s_mov_b32 s80, s73
	s_waitcnt lgkmcnt(0)
	v_mfma_f32_32x32x16_bf16 v[32:47], v[4:7], v[108:111], v[32:47]
	ds_read_b128 v[0:3], v197 offset:32768
	ds_read_b128 v[4:7], v197 offset:40960
	s_mov_b32 s81, s73
	s_mov_b32 s82, s73
	s_mov_b32 s83, s73
	s_mov_b32 s84, s73
	s_mov_b32 s85, s73
	s_mov_b32 s86, s73
	s_waitcnt vmcnt(5) lgkmcnt(1)
	v_mfma_f32_32x32x16_bf16 v[16:31], v[0:3], v[120:123], v[16:31]
	v_or_b32_e32 v0, 0x60, v208
	v_bitop3_b32 v0, v0, v68, v69 bitop3:0xde
	v_add_u32_e32 v196, 0, v0
	s_mov_b32 s87, s73
	v_lshl_add_u32 v185, v179, 2, v184
	v_mov_b32_e32 v186, 0
	s_waitcnt lgkmcnt(0)
	v_mfma_f32_32x32x16_bf16 v[32:47], v[4:7], v[120:123], v[32:47]
	ds_read_b128 v[0:3], v196 offset:32768
	ds_read_b128 v[4:7], v196 offset:40960
	s_waitcnt vmcnt(4) lgkmcnt(1)
	v_mfma_f32_32x32x16_bf16 v[16:31], v[0:3], v[124:127], v[16:31]
	v_or_b32_e32 v0, 0x80, v208
	v_bitop3_b32 v0, v0, v68, v69 bitop3:0xde
	v_add_u32_e32 v194, 0, v0
	ds_read_b128 v[0:3], v194 offset:32768
	s_waitcnt lgkmcnt(1)
	v_mfma_f32_32x32x16_bf16 v[32:47], v[4:7], v[124:127], v[32:47]
	ds_read_b128 v[4:7], v194 offset:40960
	s_waitcnt vmcnt(3) lgkmcnt(1)
; #define SLOAD(i, k0) do { sr_[i].vs0 = St::ld8(&Vh[(long)((k0) + sr) * LDK + sc]); sr_[i].vs1 = St::ld8(&Vh[(long)((k0) + 32 + sr) * LDK + sc]); \
;     sr_[i].ks0 = St::ld8(&Kh[(long)((k0) + sr) * LDK + sc]); sr_[i].ks1 = St::ld8(&Kh[(long)((k0) + 32 + sr) * LDK + sc]); } while (0)
; #define SWAIT() do { if constexpr (SDEPTH == 2) asm volatile("s_waitcnt vmcnt(4)" ::: "memory"); else asm volatile("s_waitcnt vmcnt(0)" ::: "memory"); } while (0)
; __device__ __forceinline__ void partialSM(f32x16& p0, f32x16& p1, float& m_reg, float& mn, float& alpha) {
;   constexpr float C = SCALE * 1.4426950408889634f;
;   float pmax = p0[0]; for (int r = 1; r < 16; ++r) pmax = fmaxf(pmax, p0[r]); for (int r = 0; r < 16; ++r) pmax = fmaxf(pmax, p1[r]);
;   { auto rr = __builtin_amdgcn_permlane32_swap(__float_as_uint(pmax), __float_as_uint(pmax), false, false);
;     pmax = fmaxf(__uint_as_float(rr[0]), __uint_as_float(rr[1])); }
;   if (__builtin_expect(__all(pmax - m_reg <= THR / SCALE), 1)) { mn = m_reg; alpha = 1.f; }
;   else { mn = fmaxf(m_reg, pmax); alpha = __builtin_amdgcn_exp2f((m_reg - mn) * C); m_reg = mn; }
;   float mnC = -mn * C;
;   for (int r = 0; r < 16; ++r) p0[r] = fmaf(p0[r], C, mnC); for (int r = 0; r < 16; ++r) p1[r] = fmaf(p1[r], C, mnC);
;   for (int r = 0; r < 16; ++r) p0[r] = __builtin_amdgcn_exp2f(p0[r]);
; template <typename TQ>
; __device__ __forceinline__ void attn_dense_body(const TQ* __restrict__ Qb, const bf16* __restrict__ Kh, const bf16* __restrict__ Vh,
;                                                 unsigned short* __restrict__ Ob, int seq, char* lds) {
;     ...
;   qkt(pA0, pA1, K_lds, qr, r32, hi); partialSM(pA0, pA1, m_reg, mnA, alA);
;   SLOAD(SO, KVBLK); if constexpr (SDEPTH == 2) { if (2 < NT) SLOAD(SE, 2 * KVBLK); }
;   SWAIT(); SWRITE(1, SO); __syncthreads();
	v_mfma_f32_32x32x16_bf16 v[16:31], v[0:3], v[116:119], v[16:31]
	v_or_b32_e32 v0, 0xa0, v208
	v_bitop3_b32 v0, v0, v68, v69 bitop3:0xde
	v_add_u32_e32 v195, 0, v0
	ds_read_b128 v[0:3], v195 offset:32768
	s_waitcnt lgkmcnt(1)
	v_mfma_f32_32x32x16_bf16 v[32:47], v[4:7], v[116:119], v[32:47]
	ds_read_b128 v[4:7], v195 offset:40960
	global_load_dwordx4 v[52:55], v[12:13], off
	global_load_dwordx4 v[56:59], v[14:15], off
	s_waitcnt vmcnt(4) lgkmcnt(1)
	v_mfma_f32_32x32x16_bf16 v[16:31], v[0:3], v[104:107], v[16:31]
	v_lshl_add_u64 v[0:1], s[38:39], 0, v[8:9]
	v_lshl_add_u64 v[2:3], s[38:39], 0, v[10:11]
	global_load_dwordx4 v[60:63], v[0:1], off
	global_load_dwordx4 v[64:67], v[2:3], off
	v_or_b32_e32 v0, 0xc0, v208
	v_bitop3_b32 v0, v0, v68, v69 bitop3:0xde
	v_add_u32_e32 v200, 0, v0
	ds_read_b128 v[0:3], v200 offset:32768
	v_lshlrev_b32_e32 v9, 1, v74
	v_and_or_b32 v8, v70, 24, v71
	s_waitcnt lgkmcnt(1)
	v_mfma_f32_32x32x16_bf16 v[32:47], v[4:7], v[104:107], v[32:47]
	v_and_b32_e32 v4, 32, v9
	v_and_b32_e32 v5, 0x100, v70
	v_or3_b32 v75, v8, v4, v5
	ds_read_b128 v[4:7], v200 offset:40960
	v_add_u32_e32 v188, s3, v75
	s_waitcnt vmcnt(5) lgkmcnt(1)
	v_mfma_f32_32x32x16_bf16 v[16:31], v[0:3], v[100:103], v[16:31]
	v_or_b32_e32 v0, 0xe0, v208
	v_bitop3_b32 v0, v0, v68, v69 bitop3:0xde
	v_add_u32_e32 v199, 0, v0
	ds_read_b128 v[0:3], v199 offset:32768
	ds_read_b128 v[68:71], v199 offset:40960
	s_waitcnt lgkmcnt(2)
	v_mfma_f32_32x32x16_bf16 v[32:47], v[4:7], v[100:103], v[32:47]
	s_waitcnt vmcnt(4) lgkmcnt(1)
	v_mfma_f32_32x32x16_bf16 v[16:31], v[0:3], v[96:99], v[16:31]
	v_mov_b64_e32 v[0:1], s[72:73]
	v_mov_b64_e32 v[14:15], s[86:87]
	v_mov_b64_e32 v[2:3], s[74:75]
	v_mov_b64_e32 v[4:5], s[76:77]
	v_mov_b64_e32 v[6:7], s[78:79]
	v_mov_b64_e32 v[8:9], s[80:81]
	v_mov_b64_e32 v[10:11], s[82:83]
	s_waitcnt lgkmcnt(0)
	v_mfma_f32_32x32x16_bf16 v[32:47], v[68:71], v[96:99], v[32:47]
	s_nop 2
	v_max_f32_e32 v68, v17, v17
	v_max_f32_e32 v69, v16, v16
	v_max_f32_e32 v68, v69, v68
	v_max3_f32 v68, v68, v18, v19
	v_max3_f32 v68, v68, v20, v21
	v_max3_f32 v68, v68, v22, v23
	v_max3_f32 v68, v68, v24, v25
	v_max3_f32 v68, v68, v26, v27
	v_max3_f32 v68, v68, v28, v29
	v_max3_f32 v68, v68, v30, v31
	v_max3_f32 v68, v68, v32, v33
	v_max3_f32 v68, v68, v34, v35
	v_max3_f32 v68, v68, v36, v37
	v_max3_f32 v68, v68, v38, v39
	v_max3_f32 v68, v68, v40, v41
	v_max3_f32 v68, v68, v42, v43
	v_max3_f32 v76, v68, v44, v45
	v_lshl_add_u64 v[68:69], v[50:51], 0, s[28:29]
	s_mov_b64 s[28:29], 0xa000
	v_lshl_add_u64 v[70:71], s[42:43], 0, v[68:69]
	v_lshl_add_u64 v[50:51], v[50:51], 0, s[28:29]
	v_lshl_add_u64 v[68:69], s[38:39], 0, v[68:69]
	v_lshl_add_u64 v[72:73], s[42:43], 0, v[50:51]
	global_load_dwordx4 v[128:131], v[70:71], off
	global_load_dwordx4 v[136:139], v[72:73], off
	v_lshl_add_u64 v[50:51], s[38:39], 0, v[50:51]
	global_load_dwordx4 v[132:135], v[68:69], off
	global_load_dwordx4 v[140:143], v[50:51], off
	v_max3_f32 v50, v76, v46, v47
	v_mov_b32_e32 v51, v50
	s_nop 1
	v_permlane32_swap_b32_e32 v50, v51
	v_max_f32_e32 v51, v51, v51
	v_max_f32_e32 v50, v50, v50
	v_max_f32_e32 v50, v50, v51
	v_add_f32_e32 v51, 0x7149f2ca, v50
	v_max_f32_e32 v50, 0xf149f2ca, v50
	v_cmp_ge_f32_e32 vcc, s4, v51
	v_sub_f32_e32 v51, 0xf149f2ca, v50
	v_mul_f32_e32 v51, 0x3e0293ee, v51
	v_exp_f32_e32 v51, v51
	s_cmp_eq_u64 vcc, exec
	s_cselect_b64 vcc, -1, 0
	s_addk_i32 s3, 0x4000
	v_cndmask_b32_e64 v201, v51, 1.0, vcc
	v_mov_b32_e32 v51, 0xf149f2ca
	v_cndmask_b32_e32 v168, v50, v51, vcc
	v_mul_f32_e32 v50, 0xbe0293ee, v168
	v_fmamk_f32 v16, v16, 0x3e0293ee, v50
	v_exp_f32_e32 v161, v16
	v_fmamk_f32 v16, v17, 0x3e0293ee, v50
	v_exp_f32_e32 v175, v16
	v_fmamk_f32 v16, v18, 0x3e0293ee, v50
	v_exp_f32_e32 v162, v16
	v_fmamk_f32 v16, v19, 0x3e0293ee, v50
	v_exp_f32_e32 v205, v16
	v_fmamk_f32 v16, v20, 0x3e0293ee, v50
	v_exp_f32_e32 v174, v16
	v_fmamk_f32 v16, v21, 0x3e0293ee, v50
	v_exp_f32_e32 v214, v16
	v_fmamk_f32 v16, v22, 0x3e0293ee, v50
	v_exp_f32_e32 v163, v16
	v_fmamk_f32 v16, v23, 0x3e0293ee, v50
	v_exp_f32_e32 v173, v16
	v_fmamk_f32 v16, v24, 0x3e0293ee, v50
	v_exp_f32_e32 v164, v16
	v_fmamk_f32 v16, v25, 0x3e0293ee, v50
	v_exp_f32_e32 v171, v16
	v_fmamk_f32 v16, v26, 0x3e0293ee, v50
	v_exp_f32_e32 v165, v16
	v_fmamk_f32 v16, v27, 0x3e0293ee, v50
	v_exp_f32_e32 v172, v16
	v_fmamk_f32 v16, v28, 0x3e0293ee, v50
	v_exp_f32_e32 v166, v16
	v_fmamk_f32 v16, v29, 0x3e0293ee, v50
	v_pk_fma_f32 v[144:145], v[46:47], s[22:23], v[50:51] op_sel_hi:[1,0,0]
	v_pk_fma_f32 v[150:151], v[44:45], s[22:23], v[50:51] op_sel_hi:[1,0,0]
	v_pk_fma_f32 v[154:155], v[42:43], s[22:23], v[50:51] op_sel_hi:[1,0,0]
	v_pk_fma_f32 v[146:147], v[40:41], s[22:23], v[50:51] op_sel_hi:[1,0,0]
	v_pk_fma_f32 v[148:149], v[38:39], s[22:23], v[50:51] op_sel_hi:[1,0,0]
	v_pk_fma_f32 v[152:153], v[36:37], s[22:23], v[50:51] op_sel_hi:[1,0,0]
	v_pk_fma_f32 v[156:157], v[34:35], s[22:23], v[50:51] op_sel_hi:[1,0,0]
	v_pk_fma_f32 v[158:159], v[32:33], s[22:23], v[50:51] op_sel_hi:[1,0,0]
	v_exp_f32_e32 v169, v16
	v_fmamk_f32 v16, v30, 0x3e0293ee, v50
	v_fmac_f32_e32 v50, 0x3e0293ee, v31
	v_add_u32_e32 v187, s3, v75
	v_readlane_b32 s3, v253, 29
	v_exp_f32_e32 v167, v16
	v_exp_f32_e32 v170, v50
	v_and_b32_e32 v16, 15, v74
	s_add_u32 s0, s3, s0
	v_readlane_b32 s3, v253, 30
	s_waitcnt vmcnt(4)
	v_lshl_or_b32 v48, v16, 4, v48
	s_addc_u32 s1, s3, s1
	v_mov_b64_e32 v[12:13], s[84:85]
	s_waitcnt vmcnt(7)
	ds_write_b128 v191, v[52:55] offset:16384
	s_waitcnt vmcnt(6)
	ds_write_b128 v192, v[56:59] offset:16384
	s_waitcnt vmcnt(5)
	ds_write_b128 v189, v[60:63] offset:49152
	s_waitcnt vmcnt(4)
	ds_write_b128 v190, v[64:67] offset:49152
	v_lshl_add_u64 v[180:181], s[0:1], 0, v[48:49]
	v_mov_b64_e32 v[62:63], v[14:15]
	v_mov_b64_e32 v[46:47], v[14:15]
	v_mov_b64_e32 v[30:31], v[14:15]
	v_readlane_b32 s84, v252, 4
	v_cmp_gt_u32_e64 s[38:39], 32, v177
	v_mov_b64_e32 v[60:61], v[12:13]
	v_mov_b64_e32 v[58:59], v[10:11]
	v_mov_b64_e32 v[56:57], v[8:9]
	v_mov_b64_e32 v[54:55], v[6:7]
	v_mov_b64_e32 v[52:53], v[4:5]
	v_mov_b64_e32 v[50:51], v[2:3]
	v_mov_b64_e32 v[48:49], v[0:1]
	v_mov_b64_e32 v[44:45], v[12:13]
	v_mov_b64_e32 v[42:43], v[10:11]
	v_mov_b64_e32 v[40:41], v[8:9]
	v_mov_b64_e32 v[38:39], v[6:7]
	v_mov_b64_e32 v[36:37], v[4:5]
	v_mov_b64_e32 v[34:35], v[2:3]
	v_mov_b64_e32 v[32:33], v[0:1]
	v_mov_b64_e32 v[28:29], v[12:13]
	v_mov_b64_e32 v[26:27], v[10:11]
	v_mov_b64_e32 v[24:25], v[8:9]
	v_mov_b64_e32 v[22:23], v[6:7]
	v_mov_b64_e32 v[20:21], v[4:5]
	v_mov_b64_e32 v[18:19], v[2:3]
	v_mov_b64_e32 v[16:17], v[0:1]
	v_readlane_b32 s85, v252, 5
	v_readlane_b32 s86, v252, 6
	s_mov_b32 s74, 0x7f800000
	s_mov_b32 s75, 0x2b000
	s_mov_b64 s[78:79], 0x800
	s_movk_i32 s77, 0x1ff
	v_readfirstlane_b32 s87, v211
	s_nop 3
	s_cmp_ge_u32 s87, 0x100
	s_cbranch_scc0 .Latt_prio_done
	s_setprio 1
.Latt_prio_done:
	s_waitcnt lgkmcnt(0)
	s_barrier
	v_readlane_b32 s87, v252, 7

; #define SBAR() __builtin_amdgcn_sched_barrier(0)
; __device__ __forceinline__ void finishSM(f32x16& p0, f32x16& p1, float alpha, float& l_reg, bf16x8& pa0, bf16x8& pa1, bf16x8& pa2, bf16x8& pa3) {
;   for (int r = 0; r < 16; ++r) p1[r] = __builtin_amdgcn_exp2f(p1[r]);
;   float ps = 0; for (int r = 0; r < 16; ++r) ps += p0[r]; for (int r = 0; r < 16; ++r) ps += p1[r];
;   { auto rr = __builtin_amdgcn_permlane32_swap(__float_as_uint(ps), __float_as_uint(ps), false, false);
;     ps = __uint_as_float(rr[0]) + __uint_as_float(rr[1]); }
;   l_reg = l_reg * alpha + ps;
;     ...
;   PK4(p0, 0, pa0); PK4(p0, 8, pa1); PK4(p1, 0, pa2); PK4(p1, 8, pa3);
; template <typename TQ>
; __device__ __forceinline__ void attn_dense_body(const TQ* __restrict__ Qb, const bf16* __restrict__ Kh, const bf16* __restrict__ Vh,
;                                                 unsigned short* __restrict__ Ob, int seq, char* lds) {
;     ...
;   SBAR(); qkt(pB0, pB1, (bf16*)((char*)K_lds + SHM_K), qr, r32, hi);
;   finishSM(pA0, pA1, alA, l_reg, pa0, pa1, pa2, pa3); SBAR();
;   pv_d0(o, vb0, pa0, pa1, pa2, pa3); partialSM(pB0, pB1, m_reg, mnB, alB);
.LBB0_88:
	s_setprio 0
	ds_read_b128 v[64:67], v193 offset:49152
	ds_read_b128 v[68:71], v193 offset:57344
	s_waitcnt lgkmcnt(1)
	v_mfma_f32_32x32x16_bf16 v[80:95], v[64:67], v[112:115], 0
	s_waitcnt lgkmcnt(0)
	v_mfma_f32_32x32x16_bf16 v[64:79], v[68:71], v[112:115], 0
	ds_read_b128 v[112:115], v198 offset:49152
	ds_read_b128 v[128:131], v198 offset:57344
	s_waitcnt lgkmcnt(1)
	v_mfma_f32_32x32x16_bf16 v[80:95], v[112:115], v[108:111], v[80:95]
	s_waitcnt lgkmcnt(0)
	v_mfma_f32_32x32x16_bf16 v[64:79], v[128:131], v[108:111], v[64:79]
	ds_read_b128 v[108:111], v197 offset:49152
	ds_read_b128 v[112:115], v197 offset:57344
	s_waitcnt lgkmcnt(1)
	v_mfma_f32_32x32x16_bf16 v[80:95], v[108:111], v[120:123], v[80:95]
	s_waitcnt lgkmcnt(0)
	v_mfma_f32_32x32x16_bf16 v[64:79], v[112:115], v[120:123], v[64:79]
	ds_read_b128 v[108:111], v196 offset:49152
	ds_read_b128 v[112:115], v196 offset:57344
	v_exp_f32_e32 v120, v144
	v_exp_f32_e32 v121, v145
	s_waitcnt lgkmcnt(1)
	v_mfma_f32_32x32x16_bf16 v[80:95], v[108:111], v[124:127], v[80:95]
	s_waitcnt lgkmcnt(0)
	v_mfma_f32_32x32x16_bf16 v[64:79], v[112:115], v[124:127], v[64:79]
	ds_read_b128 v[108:111], v194 offset:49152
	ds_read_b128 v[112:115], v194 offset:57344
	s_waitcnt lgkmcnt(1)
	v_mfma_f32_32x32x16_bf16 v[80:95], v[108:111], v[116:119], v[80:95]
	s_waitcnt lgkmcnt(0)
	v_mfma_f32_32x32x16_bf16 v[64:79], v[112:115], v[116:119], v[64:79]
	ds_read_b128 v[108:111], v195 offset:49152
	ds_read_b128 v[112:115], v195 offset:57344
	v_exp_f32_e32 v116, v154
	v_exp_f32_e32 v117, v155
	v_exp_f32_e32 v118, v150
	v_exp_f32_e32 v119, v151
	s_waitcnt lgkmcnt(1)
	v_mfma_f32_32x32x16_bf16 v[80:95], v[108:111], v[104:107], v[80:95]
	s_waitcnt lgkmcnt(0)
	v_mfma_f32_32x32x16_bf16 v[64:79], v[112:115], v[104:107], v[64:79]
	ds_read_b128 v[104:107], v200 offset:49152
	ds_read_b128 v[108:111], v200 offset:57344
	v_exp_f32_e32 v112, v148
	v_exp_f32_e32 v113, v149
	v_exp_f32_e32 v114, v146
	v_exp_f32_e32 v115, v147
	s_waitcnt lgkmcnt(1)
	v_mfma_f32_32x32x16_bf16 v[80:95], v[104:107], v[100:103], v[80:95]
	s_waitcnt lgkmcnt(0)
	v_mfma_f32_32x32x16_bf16 v[64:79], v[108:111], v[100:103], v[64:79]
	ds_read_b128 v[100:103], v199 offset:49152
	ds_read_b128 v[104:107], v199 offset:57344
	v_exp_f32_e32 v108, v156
	v_exp_f32_e32 v109, v157
	v_exp_f32_e32 v110, v152
	v_exp_f32_e32 v111, v153
	s_waitcnt lgkmcnt(1)
	v_mfma_f32_32x32x16_bf16 v[80:95], v[100:103], v[96:99], v[80:95]
	s_waitcnt lgkmcnt(0)
	v_mfma_f32_32x32x16_bf16 v[64:79], v[104:107], v[96:99], v[64:79]
	v_add_f32_e32 v96, 0, v161
	v_add_f32_e32 v96, v175, v96
	v_add_f32_e32 v96, v162, v96
	v_add_f32_e32 v96, v205, v96
	v_add_f32_e32 v96, v174, v96
	v_add_f32_e32 v96, v214, v96
	v_add_f32_e32 v96, v163, v96
	v_add_f32_e32 v96, v173, v96
	v_add_f32_e32 v96, v164, v96
	v_add_f32_e32 v96, v171, v96
	v_add_f32_e32 v96, v165, v96
	v_add_f32_e32 v96, v172, v96
	v_exp_f32_e32 v106, v158
	v_add_f32_e32 v96, v166, v96
	v_exp_f32_e32 v107, v159
	v_add_f32_e32 v96, v169, v96
	v_add_f32_e32 v96, v167, v96
	v_add_f32_e32 v96, v170, v96
	v_add_f32_e32 v96, v106, v96
	v_add_f32_e32 v96, v107, v96
	v_add_f32_e32 v96, v108, v96
	v_add_f32_e32 v96, v109, v96
	v_add_f32_e32 v96, v110, v96
	v_add_f32_e32 v96, v111, v96
	v_add_f32_e32 v96, v112, v96
	v_add_f32_e32 v96, v113, v96
	v_add_f32_e32 v96, v114, v96
	v_add_f32_e32 v96, v115, v96
	v_add_f32_e32 v96, v116, v96
	v_add_f32_e32 v96, v117, v96
	v_add_f32_e32 v96, v118, v96
	v_add_f32_e32 v96, v119, v96
	v_add_f32_e32 v96, v120, v96
	v_add_f32_e32 v100, v121, v96
	v_mov_b32_e32 v101, v100
	v_cvt_pk_bf16_f32 v96, v161, v175
	v_cvt_pk_bf16_f32 v97, v162, v205
	v_cvt_pk_bf16_f32 v98, v174, v214
	v_cvt_pk_bf16_f32 v99, v163, v173
	s_nop 1
	v_permlane32_swap_b32_e32 v100, v101
	v_permlane32_swap_b32_e32 v96, v98
	v_permlane32_swap_b32_e32 v97, v99
	v_cvt_pk_bf16_f32 v102, v164, v171
	v_cvt_pk_bf16_f32 v103, v165, v172
	v_cvt_pk_bf16_f32 v104, v166, v169
	v_cvt_pk_bf16_f32 v105, v167, v170
	v_cvt_pk_bf16_f32 v106, v106, v107
	v_cvt_pk_bf16_f32 v107, v108, v109
	v_cvt_pk_bf16_f32 v108, v110, v111
	v_cvt_pk_bf16_f32 v109, v112, v113
	v_cvt_pk_bf16_f32 v110, v114, v115
	v_cvt_pk_bf16_f32 v111, v116, v117
	v_cvt_pk_bf16_f32 v112, v118, v119
	v_cvt_pk_bf16_f32 v113, v120, v121
	s_nop 0
	v_permlane32_swap_b32_e32 v102, v104
	v_permlane32_swap_b32_e32 v103, v105
	v_permlane32_swap_b32_e32 v106, v108
	v_permlane32_swap_b32_e32 v107, v109
	v_permlane32_swap_b32_e32 v110, v112
	v_permlane32_swap_b32_e32 v111, v113
	ds_read_b64_tr_b16 v[114:115], v188 offset:0
	ds_read_b64_tr_b16 v[116:117], v188 offset:0x800
	ds_read_b64_tr_b16 v[118:119], v188 offset:0x1000
	ds_read_b64_tr_b16 v[120:121], v188 offset:0x1800
	ds_read_b64_tr_b16 v[122:123], v188 offset:0x2000
	ds_read_b64_tr_b16 v[124:125], v188 offset:0x2800
	ds_read_b64_tr_b16 v[126:127], v188 offset:0x3000
	ds_read_b64_tr_b16 v[128:129], v188 offset:0x3800
	s_waitcnt lgkmcnt(0)
; #define SBAR() __builtin_amdgcn_sched_barrier(0)
; #define RESC(a) do { if (__any((a) < 1.f)) { if (hi == 0) al_l[r32] = (a); asm volatile("s_waitcnt lgkmcnt(0)" ::: "memory"); \
;     for (int d = 0; d < 4; ++d) for (int r = 0; r < 16; ++r) o[d][r] *= al_l[crow(r, hi)]; } } while (0)
; template <int D0> __device__ __forceinline__ void pv_one(f32x16& od, int vb, bf16x8 pa0, bf16x8 pa1, bf16x8 pa2, bf16x8 pa3) {
;   const s16x4 l0 = tr_read<v_rd_off(D0, 0, 0)>(vb), h0 = tr_read<v_rd_off(D0, 0, 1)>(vb), l1 = tr_read<v_rd_off(D0, 1, 0)>(vb), h1 = tr_read<v_rd_off(D0, 1, 1)>(vb);
;   const s16x4 l2 = tr_read<v_rd_off(D0, 2, 0)>(vb), h2 = tr_read<v_rd_off(D0, 2, 1)>(vb), l3 = tr_read<v_rd_off(D0, 3, 0)>(vb), h3 = tr_read<v_rd_off(D0, 3, 1)>(vb);
;   asm volatile("s_waitcnt lgkmcnt(0)" ::: "memory"); SBAR();
;     ...
;   od = __builtin_amdgcn_mfma_f32_32x32x16_bf16(pa0, PK(l0, h0), od, 0, 0, 0);
;   od = __builtin_amdgcn_mfma_f32_32x32x16_bf16(pa1, PK(l1, h1), od, 0, 0, 0);
;   od = __builtin_amdgcn_mfma_f32_32x32x16_bf16(pa2, PK(l2, h2), od, 0, 0, 0);
;   od = __builtin_amdgcn_mfma_f32_32x32x16_bf16(pa3, PK(l3, h3), od, 0, 0, 0);
;     ...
; }
; __device__ __forceinline__ void pv_d0(f32x16* o, int vb, bf16x8 pa0, bf16x8 pa1, bf16x8 pa2, bf16x8 pa3) {
;   pv_one<0>(o[0], vb, pa0, pa1, pa2, pa3); pv_one<1>(o[1], vb, pa0, pa1, pa2, pa3); pv_one<2>(o[2], vb, pa0, pa1, pa2, pa3); pv_one<3>(o[3], vb, pa0, pa1, pa2, pa3);
; template <typename TQ>
; __device__ __forceinline__ void attn_dense_body(const TQ* __restrict__ Qb, const bf16* __restrict__ Kh, const bf16* __restrict__ Vh,
;                                                 unsigned short* __restrict__ Ob, int seq, char* lds) {
;     ...
;   pv_d0(o, vb0, pa0, pa1, pa2, pa3); partialSM(pB0, pB1, m_reg, mnB, alB);
;   __syncthreads(); RESC(alB);
	s_nop 0
	v_mfma_f32_32x32x16_bf16 v[0:15], v[96:99], v[114:117], v[0:15]
	ds_read_b64_tr_b16 v[114:115], v188 offset:0x200
	ds_read_b64_tr_b16 v[116:117], v188 offset:0xa00
	v_mfma_f32_32x32x16_bf16 v[0:15], v[102:105], v[118:121], v[0:15]
	ds_read_b64_tr_b16 v[118:119], v188 offset:0x1200
	ds_read_b64_tr_b16 v[120:121], v188 offset:0x1a00
	v_mfma_f32_32x32x16_bf16 v[0:15], v[106:109], v[122:125], v[0:15]
	ds_read_b64_tr_b16 v[122:123], v188 offset:0x2200
	ds_read_b64_tr_b16 v[124:125], v188 offset:0x2a00
	v_mfma_f32_32x32x16_bf16 v[0:15], v[110:113], v[126:129], v[0:15]
	ds_read_b64_tr_b16 v[126:127], v188 offset:0x3200
	ds_read_b64_tr_b16 v[128:129], v188 offset:0x3a00
	s_waitcnt lgkmcnt(0)
	v_mfma_f32_32x32x16_bf16 v[48:63], v[96:99], v[114:117], v[48:63]
	ds_read_b64_tr_b16 v[114:115], v188 offset:0x400
	ds_read_b64_tr_b16 v[116:117], v188 offset:0xc00
	v_mfma_f32_32x32x16_bf16 v[48:63], v[102:105], v[118:121], v[48:63]
	ds_read_b64_tr_b16 v[118:119], v188 offset:0x1400
	ds_read_b64_tr_b16 v[120:121], v188 offset:0x1c00
	v_mfma_f32_32x32x16_bf16 v[48:63], v[106:109], v[122:125], v[48:63]
	ds_read_b64_tr_b16 v[122:123], v188 offset:0x2400
	ds_read_b64_tr_b16 v[124:125], v188 offset:0x2c00
	v_mfma_f32_32x32x16_bf16 v[48:63], v[110:113], v[126:129], v[48:63]
	ds_read_b64_tr_b16 v[126:127], v188 offset:0x3400
	ds_read_b64_tr_b16 v[128:129], v188 offset:0x3c00
	s_waitcnt lgkmcnt(0)
	v_mfma_f32_32x32x16_bf16 v[32:47], v[96:99], v[114:117], v[32:47]
	ds_read_b64_tr_b16 v[114:115], v188 offset:0x600
	ds_read_b64_tr_b16 v[116:117], v188 offset:0xe00
	v_mfma_f32_32x32x16_bf16 v[32:47], v[102:105], v[118:121], v[32:47]
	ds_read_b64_tr_b16 v[118:119], v188 offset:0x1600
	ds_read_b64_tr_b16 v[120:121], v188 offset:0x1e00
	v_mfma_f32_32x32x16_bf16 v[32:47], v[106:109], v[122:125], v[32:47]
	ds_read_b64_tr_b16 v[122:123], v188 offset:0x2600
	ds_read_b64_tr_b16 v[124:125], v188 offset:0x2e00
	v_mfma_f32_32x32x16_bf16 v[32:47], v[110:113], v[126:129], v[32:47]
	ds_read_b64_tr_b16 v[126:127], v188 offset:0x3600
	ds_read_b64_tr_b16 v[128:129], v188 offset:0x3e00
	s_waitcnt lgkmcnt(0)
	v_mfma_f32_32x32x16_bf16 v[16:31], v[96:99], v[114:117], v[16:31]
	v_max_f32_e32 v96, v81, v81
	v_max_f32_e32 v97, v80, v80
	v_max_f32_e32 v96, v97, v96
	v_max3_f32 v96, v96, v82, v83
	v_max3_f32 v96, v96, v84, v85
	v_max3_f32 v96, v96, v86, v87
	v_max3_f32 v96, v96, v88, v89
	v_max3_f32 v96, v96, v90, v91
	v_max3_f32 v96, v96, v92, v93
	v_mfma_f32_32x32x16_bf16 v[16:31], v[102:105], v[118:121], v[16:31]
	v_max3_f32 v96, v96, v94, v95
	v_max3_f32 v96, v96, v64, v65
	v_max3_f32 v96, v96, v66, v67
	v_max3_f32 v96, v96, v68, v69
	v_max3_f32 v96, v96, v70, v71
	v_max3_f32 v96, v96, v72, v73
	v_max3_f32 v96, v96, v74, v75
	v_max3_f32 v96, v96, v76, v77
	v_mfma_f32_32x32x16_bf16 v[16:31], v[106:109], v[122:125], v[16:31]
	v_max3_f32 v96, v96, v78, v79
	v_mov_b32_e32 v97, v96
	s_nop 1
	v_permlane32_swap_b32_e32 v96, v97
	v_max_f32_e32 v97, v97, v97
	v_max_f32_e32 v96, v96, v96
	v_max_f32_e32 v96, v96, v97
	v_sub_f32_e32 v97, v96, v168
	v_cmp_ge_f32_e32 vcc, s4, v97
	v_max_f32_e32 v97, v168, v168
	v_max_f32_e32 v97, v97, v96
	v_mfma_f32_32x32x16_bf16 v[16:31], v[110:113], v[126:129], v[16:31]
	v_sub_f32_e32 v96, v168, v97
	v_mul_f32_e32 v96, 0x3e0293ee, v96
	v_exp_f32_e32 v96, v96
	s_cmp_eq_u64 vcc, exec
	s_cselect_b64 s[0:1], -1, 0
	v_cndmask_b32_e64 v96, v96, 1.0, s[0:1]
	v_cmp_gt_f32_e32 vcc, 1.0, v96
	s_barrier
	s_cbranch_vccz .LBB0_92
	s_mov_b64 s[42:43], exec
	s_and_b64 s[28:29], s[42:43], s[38:39]
	v_mov_b64_e32 v[228:229], v[242:243]
	v_mov_b64_e32 v[230:231], v[218:219]
	s_mov_b64 exec, s[28:29]
	ds_write_b32 v185, v96 offset:128
	s_or_b64 exec, exec, s[42:43]
	s_waitcnt lgkmcnt(0)
	v_add_u32_e32 v98, v184, v208
	ds_read_b128 v[102:105], v98 offset:224
	ds_read_b128 v[106:109], v98 offset:192
	ds_read_b128 v[110:113], v98 offset:160
	ds_read_b128 v[114:117], v98 offset:128
	s_waitcnt lgkmcnt(3)
	v_pk_mul_f32 v[12:13], v[12:13], v[102:103]
	s_waitcnt lgkmcnt(2)
	v_pk_mul_f32 v[8:9], v[8:9], v[106:107]
	s_waitcnt lgkmcnt(1)
	v_pk_mul_f32 v[4:5], v[4:5], v[110:111]
	v_pk_mul_f32 v[14:15], v[14:15], v[104:105]
	v_pk_mul_f32 v[10:11], v[10:11], v[108:109]
	v_pk_mul_f32 v[6:7], v[6:7], v[112:113]
	s_waitcnt lgkmcnt(0)
	v_pk_mul_f32 v[2:3], v[2:3], v[116:117]
	v_pk_mul_f32 v[0:1], v[0:1], v[114:115]
	v_pk_mul_f32 v[60:61], v[60:61], v[102:103]
	v_pk_mul_f32 v[56:57], v[56:57], v[106:107]
	v_pk_mul_f32 v[52:53], v[52:53], v[110:111]
	v_pk_mul_f32 v[62:63], v[62:63], v[104:105]
	v_pk_mul_f32 v[58:59], v[58:59], v[108:109]
	v_pk_mul_f32 v[54:55], v[54:55], v[112:113]
	v_pk_mul_f32 v[50:51], v[50:51], v[116:117]
	v_pk_mul_f32 v[48:49], v[48:49], v[114:115]
	v_pk_mul_f32 v[44:45], v[44:45], v[102:103]
	v_pk_mul_f32 v[40:41], v[40:41], v[106:107]
	v_pk_mul_f32 v[36:37], v[36:37], v[110:111]
	v_pk_mul_f32 v[46:47], v[46:47], v[104:105]
	v_pk_mul_f32 v[42:43], v[42:43], v[108:109]
	v_pk_mul_f32 v[38:39], v[38:39], v[112:113]
	v_pk_mul_f32 v[34:35], v[34:35], v[116:117]
	v_pk_mul_f32 v[32:33], v[32:33], v[114:115]
	v_pk_mul_f32 v[28:29], v[28:29], v[102:103]
	v_pk_mul_f32 v[24:25], v[24:25], v[106:107]
	v_pk_mul_f32 v[20:21], v[20:21], v[110:111]
	v_pk_mul_f32 v[30:31], v[30:31], v[104:105]
	v_pk_mul_f32 v[26:27], v[26:27], v[108:109]
	v_pk_mul_f32 v[22:23], v[22:23], v[112:113]
	v_pk_mul_f32 v[18:19], v[18:19], v[116:117]
	v_pk_mul_f32 v[16:17], v[16:17], v[114:115]
	s_branch .LBB0_93
